# GEMM first-unit prologue (8 rstd phases): compiler's full vmcnt drain in the middle of the second stage group replaced by the count the row-sum loads need (they were already complete)
# baseline (speedup 1.0000x reference)
.LBB0_539:
	s_mov_b64 s[20:21], 0x80
	s_add_i32 m0, s17, 0x18000
	v_lshl_add_u64 v[26:27], v[26:27], 0, s[20:21]
	s_waitcnt vmcnt(2)
	s_barrier
	global_load_lds_dwordx4 v[26:27], off
	v_lshl_add_u64 v[24:25], v[24:25], 0, s[20:21]
	s_add_i32 m0, s17, 0x1a000
	s_add_i32 s66, s17, 0x8000
	s_add_i32 s67, s17, 0xa000
	global_load_lds_dwordx4 v[24:25], off
	v_lshl_add_u64 v[20:21], v[20:21], 0, s[20:21]
	s_mov_b32 m0, s66
	s_add_u32 s0, s8, 0x80080
	global_load_lds_dwordx4 v[20:21], off
	v_lshl_add_u64 v[20:21], v[22:23], 0, s[20:21]
	s_mov_b32 m0, s67
	s_addc_u32 s1, s9, 0
	global_load_lds_dwordx4 v[20:21], off
	s_add_i32 m0, s17, 0x1c000
	v_lshl_add_u64 v[20:21], s[0:1], 0, v[150:151]
	global_load_lds_dwordx4 v[20:21], off
	v_lshl_add_u64 v[20:21], s[0:1], 0, v[154:155]
	s_add_i32 m0, s17, 0x1e000
	s_waitcnt vmcnt(7)
	v_pk_add_f32 v[10:11], v[14:15], v[10:11]
	global_load_lds_dwordx4 v[20:21], off
	v_pk_add_f32 v[8:9], v[12:13], v[8:9]
	v_pk_add_f32 v[0:1], v[4:5], v[0:1]
	v_pk_add_f32 v[2:3], v[6:7], v[2:3]
	v_pk_add_f32 v[0:1], v[8:9], v[0:1]
	v_pk_add_f32 v[2:3], v[10:11], v[2:3]
	v_add_f32_e32 v0, v0, v1
	v_add_f32_e32 v1, v2, v3
	v_add_f32_e32 v2, v0, v1
	v_mbcnt_lo_u32_b32 v0, -1, 0
	v_mbcnt_hi_u32_b32 v0, -1, v0
	v_and_b32_e32 v1, 64, v0
	v_xor_b32_e32 v3, 1, v0
	v_add_u32_e32 v1, 64, v1
	v_cmp_lt_i32_e32 vcc, v3, v1
	s_waitcnt vmcnt(6)
	v_writelane_b32 v253, s68, 5
	v_cmp_eq_u32_e64 s[0:1], 0, v35
	v_cndmask_b32_e32 v3, v0, v3, vcc
	v_lshlrev_b32_e32 v202, 2, v3
	s_nop 1
	v_mov_b32_dpp v3, v2 quad_perm:[1,0,3,2] row_mask:0xf bank_mask:0xf
	s_barrier
	s_and_saveexec_b64 s[4:5], s[0:1]
	s_cbranch_execz .LBB0_541
	s_waitcnt lgkmcnt(0)
	v_add_f32_e32 v2, v2, v3
	v_mov_b32_e32 v3, 0x358637bd
	v_fmac_f32_e32 v3, 0x3a000000, v2
	s_mov_b32 s26, 0x800000
	v_mul_f32_e32 v2, 0x4b800000, v3
	v_cmp_gt_f32_e32 vcc, s26, v3
	s_nop 1
	v_cndmask_b32_e32 v2, v3, v2, vcc
	v_rsq_f32_e32 v2, v2
	s_nop 0
	v_mul_f32_e32 v3, 0x45800000, v2
	v_cndmask_b32_e32 v2, v2, v3, vcc
	v_lshl_add_u32 v3, v18, 2, 0
	v_add_u32_e32 v3, 0x20000, v3
	ds_write_b32 v3, v2

.LBB0_1758:
	v_lshl_add_u64 v[22:23], s[64:65], 0, v[144:145]
	v_mov_b32_e32 v157, v145
	v_lshl_add_u64 v[24:25], s[64:65], 0, v[156:157]
	v_mov_b32_e32 v153, v145
	s_add_i32 m0, s7, 0x18000
	v_lshl_add_u64 v[22:23], v[22:23], 0, s[44:45]
	v_lshl_add_u64 v[26:27], s[62:63], 0, v[152:153]
	v_mov_b32_e32 v155, v145
	s_waitcnt vmcnt(2)
	s_barrier
	global_load_lds_dwordx4 v[22:23], off
	v_lshl_add_u64 v[22:23], v[24:25], 0, s[44:45]
	s_add_i32 m0, s7, 0x1a000
	s_add_i32 s11, s7, 0x8000
	s_add_i32 s12, s7, 0xa000
	v_lshl_add_u64 v[28:29], s[62:63], 0, v[154:155]
	global_load_lds_dwordx4 v[22:23], off
	v_lshl_add_u64 v[22:23], v[26:27], 0, s[44:45]
	s_mov_b32 m0, s11
	s_add_u32 s26, s64, 0x80080
	global_load_lds_dwordx4 v[22:23], off
	v_lshl_add_u64 v[22:23], v[28:29], 0, s[44:45]
	s_mov_b32 m0, s12
	s_addc_u32 s27, s65, 0
	global_load_lds_dwordx4 v[22:23], off
	s_add_i32 m0, s7, 0x1c000
	v_lshl_add_u64 v[22:23], s[26:27], 0, v[144:145]
	global_load_lds_dwordx4 v[22:23], off
	v_lshl_add_u64 v[22:23], s[26:27], 0, v[156:157]
	s_add_i32 m0, s7, 0x1e000
	s_waitcnt vmcnt(7)
	v_pk_add_f32 v[10:11], v[14:15], v[10:11]
	global_load_lds_dwordx4 v[22:23], off
	v_pk_add_f32 v[8:9], v[12:13], v[8:9]
	v_pk_add_f32 v[0:1], v[4:5], v[0:1]
	v_pk_add_f32 v[2:3], v[6:7], v[2:3]
	v_pk_add_f32 v[0:1], v[8:9], v[0:1]
	v_pk_add_f32 v[2:3], v[10:11], v[2:3]
	v_add_f32_e32 v0, v0, v1
	v_add_f32_e32 v1, v2, v3
	v_and_b32_e32 v2, 64, v204
	v_add_f32_e32 v0, v0, v1
	v_xor_b32_e32 v1, 1, v204
	v_add_u32_e32 v2, 64, v2
	v_cmp_lt_i32_e32 vcc, v1, v2
	s_waitcnt vmcnt(6)
	v_cmp_eq_u32_e64 s[34:35], 0, v17
	s_barrier
	v_cndmask_b32_e32 v1, v204, v1, vcc
	v_lshlrev_b32_e32 v167, 2, v1
	s_nop 1
	v_mov_b32_dpp v1, v0 quad_perm:[1,0,3,2] row_mask:0xf bank_mask:0xf
	s_and_saveexec_b64 s[26:27], s[34:35]
	s_cbranch_execz .LBB0_1760
	s_waitcnt lgkmcnt(0)
	v_add_f32_e32 v0, v0, v1
	v_fmamk_f32 v0, v0, 0x3a000000, v164
	v_cmp_gt_f32_e32 vcc, s78, v0
	v_mul_f32_e32 v1, 0x4b800000, v0
	s_nop 0
	v_cndmask_b32_e32 v0, v0, v1, vcc
	v_rsq_f32_e32 v0, v0
	s_nop 0
	v_mul_f32_e32 v1, 0x45800000, v0
	v_cndmask_b32_e32 v0, v0, v1, vcc
	v_lshl_add_u32 v1, v16, 2, 0
	v_add_u32_e32 v1, 0x20000, v1
	ds_write_b32 v1, v0

.LBB0_2120:
	s_mov_b64 s[48:49], 0x80
	s_add_i32 m0, s7, 0x18000
	v_lshl_add_u64 v[26:27], v[26:27], 0, s[48:49]
	s_waitcnt vmcnt(2)
	s_barrier
	global_load_lds_dwordx4 v[26:27], off
	v_lshl_add_u64 v[24:25], v[24:25], 0, s[48:49]
	s_add_i32 m0, s7, 0x1a000
	s_add_i32 s11, s7, 0x8000
	s_add_i32 s12, s7, 0xa000
	global_load_lds_dwordx4 v[24:25], off
	v_lshl_add_u64 v[20:21], v[20:21], 0, s[48:49]
	s_mov_b32 m0, s11
	s_add_u32 s28, s40, 0x80080
	global_load_lds_dwordx4 v[20:21], off
	v_lshl_add_u64 v[20:21], v[22:23], 0, s[48:49]
	s_mov_b32 m0, s12
	s_addc_u32 s29, s41, 0
	global_load_lds_dwordx4 v[20:21], off
	s_add_i32 m0, s7, 0x1c000
	v_lshl_add_u64 v[20:21], s[28:29], 0, v[150:151]
	global_load_lds_dwordx4 v[20:21], off
	v_lshl_add_u64 v[20:21], s[28:29], 0, v[154:155]
	s_add_i32 m0, s7, 0x1e000
	s_waitcnt vmcnt(7)
	v_pk_add_f32 v[10:11], v[14:15], v[10:11]
	global_load_lds_dwordx4 v[20:21], off
	v_pk_add_f32 v[8:9], v[12:13], v[8:9]
	v_pk_add_f32 v[0:1], v[4:5], v[0:1]
	v_pk_add_f32 v[2:3], v[6:7], v[2:3]
	v_pk_add_f32 v[0:1], v[8:9], v[0:1]
	v_pk_add_f32 v[2:3], v[10:11], v[2:3]
	v_add_f32_e32 v0, v0, v1
	v_add_f32_e32 v1, v2, v3
	v_and_b32_e32 v2, 64, v204
	v_add_f32_e32 v0, v0, v1
	v_xor_b32_e32 v1, 1, v204
	v_add_u32_e32 v2, 64, v2
	v_cmp_lt_i32_e32 vcc, v1, v2
	s_waitcnt vmcnt(6)
	s_mov_b32 s51, 0
	v_cmp_eq_u32_e64 s[34:35], 0, v17
	v_cndmask_b32_e32 v1, v204, v1, vcc
	v_lshlrev_b32_e32 v194, 2, v1
	s_nop 1
	v_mov_b32_dpp v1, v0 quad_perm:[1,0,3,2] row_mask:0xf bank_mask:0xf
	s_barrier
	s_and_saveexec_b64 s[38:39], s[34:35]
	s_cbranch_execz .LBB0_2122
	s_waitcnt lgkmcnt(0)
	v_add_f32_e32 v0, v0, v1
	v_mov_b32_e32 v1, 0x358637bd
	v_fmac_f32_e32 v1, 0x3a000000, v0
	s_mov_b32 s13, 0x800000
	v_mul_f32_e32 v0, 0x4b800000, v1
	v_cmp_gt_f32_e32 vcc, s13, v1
	s_nop 1
	v_cndmask_b32_e32 v0, v1, v0, vcc
	v_rsq_f32_e32 v0, v0
	s_nop 0
	v_mul_f32_e32 v1, 0x45800000, v0
	v_cndmask_b32_e32 v0, v0, v1, vcc
	v_lshl_add_u32 v1, v16, 2, 0
	v_add_u32_e32 v1, 0x20000, v1
	ds_write_b32 v1, v0

.LBB0_3122:
	v_lshl_add_u64 v[22:23], s[62:63], 0, v[144:145]
	v_mov_b32_e32 v157, v145
	v_lshl_add_u64 v[24:25], s[62:63], 0, v[156:157]
	v_mov_b32_e32 v153, v145
	s_add_i32 m0, s7, 0x18000
	v_lshl_add_u64 v[22:23], v[22:23], 0, s[42:43]
	v_lshl_add_u64 v[26:27], s[60:61], 0, v[152:153]
	v_mov_b32_e32 v155, v145
	s_waitcnt vmcnt(2)
	s_barrier
	global_load_lds_dwordx4 v[22:23], off
	v_lshl_add_u64 v[22:23], v[24:25], 0, s[42:43]
	s_add_i32 m0, s7, 0x1a000
	s_add_i32 s11, s7, 0x8000
	s_add_i32 s12, s7, 0xa000
	v_lshl_add_u64 v[28:29], s[60:61], 0, v[154:155]
	global_load_lds_dwordx4 v[22:23], off
	v_lshl_add_u64 v[22:23], v[26:27], 0, s[42:43]
	s_mov_b32 m0, s11
	s_add_u32 s26, s62, 0x80080
	global_load_lds_dwordx4 v[22:23], off
	v_lshl_add_u64 v[22:23], v[28:29], 0, s[42:43]
	s_mov_b32 m0, s12
	s_addc_u32 s27, s63, 0
	global_load_lds_dwordx4 v[22:23], off
	s_add_i32 m0, s7, 0x1c000
	v_lshl_add_u64 v[22:23], s[26:27], 0, v[144:145]
	global_load_lds_dwordx4 v[22:23], off
	v_lshl_add_u64 v[22:23], s[26:27], 0, v[156:157]
	s_add_i32 m0, s7, 0x1e000
	s_waitcnt vmcnt(7)
	v_pk_add_f32 v[10:11], v[14:15], v[10:11]
	global_load_lds_dwordx4 v[22:23], off
	v_pk_add_f32 v[8:9], v[12:13], v[8:9]
	v_pk_add_f32 v[0:1], v[4:5], v[0:1]
	v_pk_add_f32 v[2:3], v[6:7], v[2:3]
	v_pk_add_f32 v[0:1], v[8:9], v[0:1]
	v_pk_add_f32 v[2:3], v[10:11], v[2:3]
	v_add_f32_e32 v0, v0, v1
	v_add_f32_e32 v1, v2, v3
	v_and_b32_e32 v2, 64, v204
	v_add_f32_e32 v0, v0, v1
	v_xor_b32_e32 v1, 1, v204
	v_add_u32_e32 v2, 64, v2
	v_cmp_lt_i32_e32 vcc, v1, v2
	s_waitcnt vmcnt(6)
	v_cmp_eq_u32_e64 s[34:35], 0, v17
	s_barrier
	v_cndmask_b32_e32 v1, v204, v1, vcc
	v_lshlrev_b32_e32 v167, 2, v1
	s_nop 1
	v_mov_b32_dpp v1, v0 quad_perm:[1,0,3,2] row_mask:0xf bank_mask:0xf
	s_and_saveexec_b64 s[26:27], s[34:35]
	s_cbranch_execz .LBB0_3124
	s_waitcnt lgkmcnt(0)
	v_add_f32_e32 v0, v0, v1
	v_fmamk_f32 v0, v0, 0x3a000000, v164
	v_cmp_gt_f32_e32 vcc, s75, v0
	v_mul_f32_e32 v1, 0x4b800000, v0
	s_nop 0
	v_cndmask_b32_e32 v0, v0, v1, vcc
	v_rsq_f32_e32 v0, v0
	s_nop 0
	v_mul_f32_e32 v1, 0x45800000, v0
	v_cndmask_b32_e32 v0, v0, v1, vcc
	v_lshl_add_u32 v1, v16, 2, 0
	v_add_u32_e32 v1, 0x20000, v1
	ds_write_b32 v1, v0

.LBB0_3731:
	s_mov_b64 s[26:27], 0x80
	s_add_i32 m0, s7, 0x18000
	v_lshl_add_u64 v[26:27], v[26:27], 0, s[26:27]
	s_waitcnt vmcnt(2)
	s_barrier
	global_load_lds_dwordx4 v[26:27], off
	v_lshl_add_u64 v[24:25], v[24:25], 0, s[26:27]
	s_add_i32 m0, s7, 0x1a000
	s_add_i32 s11, s7, 0x8000
	s_add_i32 s12, s7, 0xa000
	global_load_lds_dwordx4 v[24:25], off
	v_lshl_add_u64 v[20:21], v[20:21], 0, s[26:27]
	s_mov_b32 m0, s11
	s_add_u32 s30, s60, 0x80080
	global_load_lds_dwordx4 v[20:21], off
	v_lshl_add_u64 v[20:21], v[22:23], 0, s[26:27]
	s_mov_b32 m0, s12
	s_addc_u32 s31, s61, 0
	global_load_lds_dwordx4 v[20:21], off
	s_add_i32 m0, s7, 0x1c000
	v_lshl_add_u64 v[20:21], s[30:31], 0, v[146:147]
	global_load_lds_dwordx4 v[20:21], off
	v_lshl_add_u64 v[20:21], s[30:31], 0, v[150:151]
	s_add_i32 m0, s7, 0x1e000
	s_waitcnt vmcnt(7)
	v_pk_add_f32 v[10:11], v[14:15], v[10:11]
	global_load_lds_dwordx4 v[20:21], off
	v_pk_add_f32 v[8:9], v[12:13], v[8:9]
	v_pk_add_f32 v[0:1], v[4:5], v[0:1]
	v_pk_add_f32 v[2:3], v[6:7], v[2:3]
	v_pk_add_f32 v[0:1], v[8:9], v[0:1]
	v_pk_add_f32 v[2:3], v[10:11], v[2:3]
	v_add_f32_e32 v0, v0, v1
	v_add_f32_e32 v1, v2, v3
	v_and_b32_e32 v2, 64, v204
	v_add_f32_e32 v0, v0, v1
	v_xor_b32_e32 v1, 1, v204
	v_add_u32_e32 v2, 64, v2
	v_cmp_lt_i32_e32 vcc, v1, v2
	s_waitcnt vmcnt(6)
	s_mov_b32 s41, 0
	v_cmp_eq_u32_e64 s[34:35], 0, v17
	v_cndmask_b32_e32 v1, v204, v1, vcc
	v_lshlrev_b32_e32 v174, 2, v1
	s_nop 1
	v_mov_b32_dpp v1, v0 quad_perm:[1,0,3,2] row_mask:0xf bank_mask:0xf
	s_barrier
	s_and_saveexec_b64 s[38:39], s[34:35]
	s_cbranch_execz .LBB0_3733
	s_waitcnt lgkmcnt(0)
	v_add_f32_e32 v0, v0, v1
	v_mov_b32_e32 v1, 0x358637bd
	v_fmac_f32_e32 v1, 0x3a000000, v0
	s_mov_b32 s30, 0x800000
	v_mul_f32_e32 v0, 0x4b800000, v1
	v_cmp_gt_f32_e32 vcc, s30, v1
	s_nop 1
	v_cndmask_b32_e32 v0, v1, v0, vcc
	v_rsq_f32_e32 v0, v0
	s_nop 0
	v_mul_f32_e32 v1, 0x45800000, v0
	v_cndmask_b32_e32 v0, v0, v1, vcc
	v_lshl_add_u32 v1, v16, 2, 0
	v_add_u32_e32 v1, 0x20000, v1
	ds_write_b32 v1, v0

.LBB0_6304:
	s_mov_b64 s[60:61], 0x80
	s_add_i32 m0, s5, 0x18000
	v_lshl_add_u64 v[26:27], v[26:27], 0, s[60:61]
	s_waitcnt vmcnt(2)
	s_barrier
	global_load_lds_dwordx4 v[26:27], off
	v_lshl_add_u64 v[24:25], v[24:25], 0, s[60:61]
	s_add_i32 m0, s5, 0x1a000
	s_add_i32 s9, s5, 0x8000
	s_add_i32 s10, s5, 0xa000
	global_load_lds_dwordx4 v[24:25], off
	v_lshl_add_u64 v[20:21], v[20:21], 0, s[60:61]
	s_mov_b32 m0, s9
	s_add_u32 s26, s20, 0x80080
	global_load_lds_dwordx4 v[20:21], off
	v_lshl_add_u64 v[20:21], v[22:23], 0, s[60:61]
	s_mov_b32 m0, s10
	s_addc_u32 s27, s21, 0
	global_load_lds_dwordx4 v[20:21], off
	s_add_i32 m0, s5, 0x1c000
	v_lshl_add_u64 v[20:21], s[26:27], 0, v[150:151]
	global_load_lds_dwordx4 v[20:21], off
	v_lshl_add_u64 v[20:21], s[26:27], 0, v[154:155]
	s_add_i32 m0, s5, 0x1e000
	s_waitcnt vmcnt(7)
	v_pk_add_f32 v[10:11], v[14:15], v[10:11]
	global_load_lds_dwordx4 v[20:21], off
	v_pk_add_f32 v[8:9], v[12:13], v[8:9]
	v_pk_add_f32 v[0:1], v[4:5], v[0:1]
	v_pk_add_f32 v[2:3], v[6:7], v[2:3]
	v_pk_add_f32 v[0:1], v[8:9], v[0:1]
	v_pk_add_f32 v[2:3], v[10:11], v[2:3]
	v_add_f32_e32 v0, v0, v1
	v_add_f32_e32 v1, v2, v3
	v_add_f32_e32 v1, v0, v1
	v_and_b32_e32 v0, 64, v204
	v_xor_b32_e32 v2, 1, v204
	v_add_u32_e32 v0, 64, v0
	v_cmp_lt_i32_e32 vcc, v2, v0
	s_waitcnt vmcnt(6)
	s_mov_b32 s63, 0
	v_cmp_eq_u32_e64 s[34:35], 0, v29
	v_cndmask_b32_e32 v2, v204, v2, vcc
	v_lshlrev_b32_e32 v198, 2, v2
	s_nop 1
	v_mov_b32_dpp v2, v1 quad_perm:[1,0,3,2] row_mask:0xf bank_mask:0xf
	s_barrier
	s_and_saveexec_b64 s[26:27], s[34:35]
	s_cbranch_execz .LBB0_6306
	s_waitcnt lgkmcnt(0)
	v_add_f32_e32 v1, v1, v2
	v_mov_b32_e32 v2, 0x358637bd
	v_fmac_f32_e32 v2, 0x3a000000, v1
	s_mov_b32 s11, 0x800000
	v_mul_f32_e32 v1, 0x4b800000, v2
	v_cmp_gt_f32_e32 vcc, s11, v2
	s_nop 1
	v_cndmask_b32_e32 v1, v2, v1, vcc
	v_rsq_f32_e32 v1, v1
	s_nop 0
	v_mul_f32_e32 v2, 0x45800000, v1
	v_cndmask_b32_e32 v1, v1, v2, vcc
	v_lshl_add_u32 v2, v18, 2, 0
	v_add_u32_e32 v2, 0x20000, v2
	ds_write_b32 v2, v1

.LBB0_7525:
	v_lshl_add_u64 v[22:23], s[66:67], 0, v[144:145]
	v_mov_b32_e32 v157, v145
	v_lshl_add_u64 v[24:25], s[66:67], 0, v[156:157]
	v_mov_b32_e32 v153, v145
	s_add_i32 m0, s63, 0x18000
	v_lshl_add_u64 v[22:23], v[22:23], 0, s[46:47]
	v_lshl_add_u64 v[26:27], s[64:65], 0, v[152:153]
	v_mov_b32_e32 v155, v145
	s_waitcnt vmcnt(2)
	s_barrier
	global_load_lds_dwordx4 v[22:23], off
	v_lshl_add_u64 v[22:23], v[24:25], 0, s[46:47]
	s_add_i32 m0, s63, 0x1a000
	s_add_i32 s87, s63, 0x8000
	s_add_i32 s88, s63, 0xa000
	v_lshl_add_u64 v[28:29], s[64:65], 0, v[154:155]
	global_load_lds_dwordx4 v[22:23], off
	v_lshl_add_u64 v[22:23], v[26:27], 0, s[46:47]
	s_mov_b32 m0, s87
	s_add_u32 s26, s66, 0x80080
	global_load_lds_dwordx4 v[22:23], off
	v_lshl_add_u64 v[22:23], v[28:29], 0, s[46:47]
	s_mov_b32 m0, s88
	s_addc_u32 s27, s67, 0
	global_load_lds_dwordx4 v[22:23], off
	s_add_i32 m0, s63, 0x1c000
	v_lshl_add_u64 v[22:23], s[26:27], 0, v[144:145]
	global_load_lds_dwordx4 v[22:23], off
	v_lshl_add_u64 v[22:23], s[26:27], 0, v[156:157]
	s_add_i32 m0, s63, 0x1e000
	s_waitcnt vmcnt(7)
	v_pk_add_f32 v[10:11], v[14:15], v[10:11]
	global_load_lds_dwordx4 v[22:23], off
	v_pk_add_f32 v[8:9], v[12:13], v[8:9]
	v_pk_add_f32 v[0:1], v[4:5], v[0:1]
	v_pk_add_f32 v[2:3], v[6:7], v[2:3]
	v_pk_add_f32 v[0:1], v[8:9], v[0:1]
	v_pk_add_f32 v[2:3], v[10:11], v[2:3]
	v_add_f32_e32 v0, v0, v1
	v_add_f32_e32 v1, v2, v3
	v_and_b32_e32 v2, 64, v204
	v_add_f32_e32 v0, v0, v1
	v_xor_b32_e32 v1, 1, v204
	v_add_u32_e32 v2, 64, v2
	v_cmp_lt_i32_e32 vcc, v1, v2
	s_waitcnt vmcnt(6)
	v_cmp_eq_u32_e64 s[34:35], 0, v17
	s_barrier
	v_cndmask_b32_e32 v1, v204, v1, vcc
	v_lshlrev_b32_e32 v166, 2, v1
	s_nop 1
	v_mov_b32_dpp v1, v0 quad_perm:[1,0,3,2] row_mask:0xf bank_mask:0xf
	s_and_saveexec_b64 s[26:27], s[34:35]
	s_cbranch_execz .LBB0_7527
	s_waitcnt lgkmcnt(0)
	v_add_f32_e32 v0, v0, v1
	v_fmamk_f32 v0, v0, 0x3a000000, v164
	v_cmp_gt_f32_e32 vcc, s92, v0
	v_mul_f32_e32 v1, 0x4b800000, v0
	s_nop 0
	v_cndmask_b32_e32 v0, v0, v1, vcc
	v_rsq_f32_e32 v0, v0
	s_nop 0
	v_mul_f32_e32 v1, 0x45800000, v0
	v_cndmask_b32_e32 v0, v0, v1, vcc
	v_lshl_add_u32 v1, v16, 2, 0
	v_add_u32_e32 v1, 0x20000, v1
	ds_write_b32 v1, v0
